# SSD sample units: first four steps of the 64-lane sum butterfly as DPP adds (bit-identical), on top of v60
# baseline (speedup 1.0000x reference)
.LBB0_394:
	s_or_b64 exec, exec, s[4:5]
	s_nop 4
	v_sub_f32_e32 v138, v229, v198
	v_sub_f32_e32 v139, v229, v199
	v_sub_f32_e32 v140, v229, v194
	v_sub_f32_e32 v141, v229, v195
	v_mul_f32_e32 v138, 0x3fb8aa3b, v138
	v_mul_f32_e32 v139, 0x3fb8aa3b, v139
	v_mul_f32_e32 v140, 0x3fb8aa3b, v140
	v_mul_f32_e32 v141, 0x3fb8aa3b, v141
	v_exp_f32_e32 v138, v138
	v_exp_f32_e32 v139, v139
	v_exp_f32_e32 v140, v140
	v_exp_f32_e32 v141, v141
	v_mul_f32_e32 v142, v196, v138
	v_mul_f32_e32 v143, v197, v139
	v_mul_f32_e32 v144, v192, v140
	v_mul_f32_e32 v145, v193, v141
	v_mul_f32_e32 v138, v142, v150
	v_mul_f32_e32 v139, v143, v151
	v_mul_f32_e32 v140, v144, v152
	v_mul_f32_e32 v141, v145, v153
	v_mul_f32_e32 v142, v142, v146
	v_mul_f32_e32 v143, v143, v147
	v_mul_f32_e32 v144, v144, v148
	v_mul_f32_e32 v145, v145, v149
	s_waitcnt vmcnt(33)
	v_and_b32_e32 v146, 0xffff, v210
	s_waitcnt vmcnt(32)
	v_and_b32_e32 v147, 0xffff, v211
	s_waitcnt vmcnt(31)
	v_and_b32_e32 v148, 0xffff, v212
	s_waitcnt vmcnt(30)
	v_and_b32_e32 v149, 0xffff, v213
	s_waitcnt vmcnt(29)
	v_and_b32_e32 v150, 0xffff, v214
	s_waitcnt vmcnt(28)
	v_and_b32_e32 v151, 0xffff, v215
	s_waitcnt vmcnt(27)
	v_and_b32_e32 v152, 0xffff, v216
	s_waitcnt vmcnt(26)
	v_and_b32_e32 v153, 0xffff, v217
	s_waitcnt vmcnt(16)
	v_and_b32_e32 v203, 0xffff, v228
	v_and_b32_e32 v185, 0xffff, v227
	v_and_b32_e32 v202, 0xffff, v226
	v_and_b32_e32 v183, 0xffff, v225
	v_and_b32_e32 v201, 0xffff, v224
	v_and_b32_e32 v181, 0xffff, v223
	v_and_b32_e32 v200, 0xffff, v222
	v_and_b32_e32 v179, 0xffff, v221
	s_waitcnt vmcnt(0)
	v_lshl_add_u32 v147, v219, 5, v232
	ds_read_b128 v[148:151], v147 offset:8192
	v_mul_f32_e32 v146, 0x3fb8aa3b, v229
	s_lshl_b32 s0, s39, 2
	v_exp_f32_e32 v146, v146
	s_add_i32 s0, s0, s16
	s_waitcnt lgkmcnt(0)
	v_cndmask_b32_e64 v148, v148, 0, vcc
	v_cndmask_b32_e64 v149, v149, 0, vcc
	v_cndmask_b32_e64 v150, v150, 0, vcc
	v_cndmask_b32_e64 v151, v151, 0, vcc
	v_cvt_pk_bf16_f32 v148, v148, v149
	v_cvt_pk_bf16_f32 v149, v150, v151
	v_mov_b32_e32 v150, v5
	v_mov_b32_e32 v151, v5
	s_lshl_b32 s1, s40, 5
	s_add_i32 s0, s0, s1
	v_cndmask_b32_e64 v138, v138, 0, vcc
	v_cndmask_b32_e64 v139, v139, 0, vcc
	v_cndmask_b32_e64 v140, v140, 0, vcc
	v_cndmask_b32_e64 v141, v141, 0, vcc
	s_ashr_i32 s1, s0, 31
	v_cvt_pk_bf16_f32 v138, v138, v139
	v_cvt_pk_bf16_f32 v139, v140, v141
	v_mov_b32_e32 v140, v5
	v_mov_b32_e32 v141, v5
	v_cndmask_b32_e64 v142, v142, 0, vcc
	v_cndmask_b32_e64 v143, v143, 0, vcc
	v_cndmask_b32_e64 v144, v144, 0, vcc
	v_cndmask_b32_e64 v145, v145, 0, vcc
	s_lshl_b64 s[0:1], s[0:1], 15
	v_pk_mul_f32 v[72:73], v[72:73], v[146:147] op_sel_hi:[1,0]
	v_pk_mul_f32 v[70:71], v[70:71], v[146:147] op_sel_hi:[1,0]
	v_cvt_pk_bf16_f32 v142, v142, v143
	v_cvt_pk_bf16_f32 v143, v144, v145
	v_mov_b32_e32 v144, v5
	v_mov_b32_e32 v145, v5
	s_add_u32 s0, s25, s0
	v_mfma_f32_16x16x32_bf16 v[70:73], v[148:151], v[138:141], v[70:73]
	v_mul_f32_e64 v68, v68, v146
	v_mul_f32_e64 v69, v69, v146
	v_pk_mul_f32 v[66:67], v[66:67], v[146:147] op_sel_hi:[1,0]
	s_addc_u32 s1, s26, s1
	v_lshl_add_u64 v[2:3], v[2:3], 2, s[0:1]
	v_mfma_f32_16x16x32_bf16 v[66:69], v[148:151], v[142:145], v[66:69]
	v_lshlrev_b32_e32 v152, 2, v220
	v_mov_b32_e32 v153, v5
	v_lshl_add_u64 v[152:153], v[2:3], 0, v[152:153]
	global_store_dwordx4 v[152:153], v[70:73], off
	v_pk_mul_f32 v[60:61], v[60:61], v[146:147] op_sel_hi:[1,0]
	v_pk_mul_f32 v[58:59], v[58:59], v[146:147] op_sel_hi:[1,0]
	v_lshl_add_u64 v[70:71], v[2:3], 0, v[4:5]
	s_nop 0
	global_store_dwordx4 v[70:71], v[66:69], off
	ds_read_b128 v[66:69], v147 offset:8704
	v_pk_mul_f32 v[52:53], v[52:53], v[146:147] op_sel_hi:[1,0]
	v_pk_mul_f32 v[50:51], v[50:51], v[146:147] op_sel_hi:[1,0]
	v_pk_mul_f32 v[44:45], v[44:45], v[146:147] op_sel_hi:[1,0]
	v_pk_mul_f32 v[42:43], v[42:43], v[146:147] op_sel_hi:[1,0]
	s_waitcnt lgkmcnt(0)
	v_cndmask_b32_e64 v2, v66, 0, vcc
	v_cndmask_b32_e64 v3, v67, 0, vcc
	v_cndmask_b32_e64 v4, v68, 0, vcc
	v_cndmask_b32_e64 v66, v69, 0, vcc
	v_cvt_pk_bf16_f32 v2, v2, v3
	v_cvt_pk_bf16_f32 v3, v4, v66
	v_mov_b32_e32 v4, v5
	v_pk_mul_f32 v[32:33], v[32:33], v[146:147] op_sel_hi:[1,0]
	v_pk_mul_f32 v[30:31], v[30:31], v[146:147] op_sel_hi:[1,0]
	v_mfma_f32_16x16x32_bf16 v[58:61], v[2:5], v[138:141], v[58:61]
	v_mul_f32_e64 v24, v24, v146
	v_mul_f32_e64 v25, v25, v146
	v_pk_mul_f32 v[22:23], v[22:23], v[146:147] op_sel_hi:[1,0]
	v_pk_mul_f32 v[16:17], v[16:17], v[146:147] op_sel_hi:[1,0]
	s_nop 3
	global_store_dwordx4 v[152:153], v[58:61], off offset:64
	v_pk_mul_f32 v[14:15], v[14:15], v[146:147] op_sel_hi:[1,0]
	v_pk_mul_f32 v[8:9], v[8:9], v[146:147] op_sel_hi:[1,0]
	v_pk_mul_f32 v[60:61], v[64:65], v[146:147] op_sel_hi:[1,0]
	v_pk_mul_f32 v[58:59], v[62:63], v[146:147] op_sel_hi:[1,0]
	v_pk_mul_f32 v[6:7], v[6:7], v[146:147] op_sel_hi:[1,0]
	v_mov_b64_e32 v[66:67], v[106:107]
	v_mfma_f32_16x16x32_bf16 v[58:61], v[2:5], v[142:145], v[58:61]
	v_mov_b64_e32 v[62:63], v[110:111]
	v_mov_b64_e32 v[68:69], v[108:109]
	v_mov_b64_e32 v[64:65], v[112:113]
	v_mov_b32_e32 v209, v218
	s_nop 3
	global_store_dwordx4 v[70:71], v[58:61], off offset:64
	ds_read_b128 v[58:61], v147 offset:9216
	s_waitcnt lgkmcnt(0)
	v_cndmask_b32_e64 v2, v58, 0, vcc
	v_cndmask_b32_e64 v3, v59, 0, vcc
	v_cndmask_b32_e64 v4, v60, 0, vcc
	v_cndmask_b32_e64 v58, v61, 0, vcc
	v_cvt_pk_bf16_f32 v2, v2, v3
	v_cvt_pk_bf16_f32 v3, v4, v58
	v_mov_b32_e32 v4, v5
	v_mov_b64_e32 v[58:59], v[78:79]
	v_mov_b64_e32 v[60:61], v[80:81]
	v_mfma_f32_16x16x32_bf16 v[50:53], v[2:5], v[138:141], v[50:53]
	s_nop 7
	global_store_dwordx4 v[152:153], v[50:53], off offset:128
	s_nop 1
	v_pk_mul_f32 v[52:53], v[56:57], v[146:147] op_sel_hi:[1,0]
	v_pk_mul_f32 v[50:51], v[54:55], v[146:147] op_sel_hi:[1,0]
	v_mov_b64_e32 v[54:55], v[114:115]
	v_mov_b64_e32 v[56:57], v[116:117]
	v_mfma_f32_16x16x32_bf16 v[50:53], v[2:5], v[142:145], v[50:53]
	s_nop 7
	global_store_dwordx4 v[70:71], v[50:53], off offset:128
	ds_read_b128 v[50:53], v147 offset:9728
	s_waitcnt lgkmcnt(0)
	v_cndmask_b32_e64 v2, v50, 0, vcc
	v_cndmask_b32_e64 v3, v51, 0, vcc
	v_cndmask_b32_e64 v4, v52, 0, vcc
	v_cndmask_b32_e64 v50, v53, 0, vcc
	v_cvt_pk_bf16_f32 v2, v2, v3
	v_cvt_pk_bf16_f32 v3, v4, v50
	v_mov_b32_e32 v4, v5
	v_mov_b64_e32 v[50:51], v[82:83]
	v_mov_b64_e32 v[52:53], v[84:85]
	v_mfma_f32_16x16x32_bf16 v[42:45], v[2:5], v[138:141], v[42:45]
	s_nop 7
	global_store_dwordx4 v[152:153], v[42:45], off offset:192
	s_nop 1
	v_pk_mul_f32 v[44:45], v[48:49], v[146:147] op_sel_hi:[1,0]
	v_pk_mul_f32 v[42:43], v[46:47], v[146:147] op_sel_hi:[1,0]
	v_mov_b64_e32 v[46:47], v[118:119]
	v_mov_b64_e32 v[48:49], v[120:121]
	v_mfma_f32_16x16x32_bf16 v[42:45], v[2:5], v[142:145], v[42:45]
	s_nop 7
	global_store_dwordx4 v[70:71], v[42:45], off offset:192
	ds_read_b128 v[42:45], v147 offset:10240
	s_waitcnt lgkmcnt(0)
	v_cndmask_b32_e64 v2, v42, 0, vcc
	v_cndmask_b32_e64 v3, v43, 0, vcc
	v_cndmask_b32_e64 v4, v44, 0, vcc
	v_cndmask_b32_e64 v42, v45, 0, vcc
	v_cvt_pk_bf16_f32 v2, v2, v3
	v_cvt_pk_bf16_f32 v3, v4, v42
	v_mov_b32_e32 v4, v5
	v_mov_b64_e32 v[42:43], v[86:87]
	v_mov_b64_e32 v[44:45], v[88:89]
	v_mfma_f32_16x16x32_bf16 v[30:33], v[2:5], v[138:141], v[30:33]
	s_nop 7
	global_store_dwordx4 v[152:153], v[30:33], off offset:256
	s_nop 1
	v_pk_mul_f32 v[32:33], v[36:37], v[146:147] op_sel_hi:[1,0]
	v_pk_mul_f32 v[30:31], v[34:35], v[146:147] op_sel_hi:[1,0]
	v_mov_b64_e32 v[34:35], v[122:123]
	v_mov_b64_e32 v[36:37], v[124:125]
	v_mfma_f32_16x16x32_bf16 v[30:33], v[2:5], v[142:145], v[30:33]
	s_nop 7
	global_store_dwordx4 v[70:71], v[30:33], off offset:256
	ds_read_b128 v[30:33], v147 offset:10752
	s_waitcnt lgkmcnt(0)
	v_cndmask_b32_e64 v2, v30, 0, vcc
	v_cndmask_b32_e64 v3, v31, 0, vcc
	v_cndmask_b32_e64 v4, v32, 0, vcc
	v_cndmask_b32_e64 v30, v33, 0, vcc
	v_cvt_pk_bf16_f32 v2, v2, v3
	v_cvt_pk_bf16_f32 v3, v4, v30
	v_mov_b32_e32 v4, v5
	v_mov_b64_e32 v[30:31], v[90:91]
	v_mov_b64_e32 v[32:33], v[92:93]
	v_mfma_f32_16x16x32_bf16 v[22:25], v[2:5], v[138:141], v[22:25]
	s_nop 7
	global_store_dwordx4 v[152:153], v[22:25], off offset:320
	s_nop 1
	v_pk_mul_f32 v[24:25], v[28:29], v[146:147] op_sel_hi:[1,0]
	v_pk_mul_f32 v[22:23], v[26:27], v[146:147] op_sel_hi:[1,0]
	v_mov_b64_e32 v[26:27], v[126:127]
	v_mov_b64_e32 v[28:29], v[128:129]
	v_mfma_f32_16x16x32_bf16 v[22:25], v[2:5], v[142:145], v[22:25]
	s_nop 7
	global_store_dwordx4 v[70:71], v[22:25], off offset:320
	ds_read_b128 v[22:25], v147 offset:11264
	s_waitcnt lgkmcnt(0)
	v_cndmask_b32_e64 v2, v22, 0, vcc
	v_cndmask_b32_e64 v3, v23, 0, vcc
	v_cndmask_b32_e64 v4, v24, 0, vcc
	v_cndmask_b32_e64 v22, v25, 0, vcc
	v_cvt_pk_bf16_f32 v2, v2, v3
	v_cvt_pk_bf16_f32 v3, v4, v22
	v_mov_b32_e32 v4, v5
	v_mov_b64_e32 v[22:23], v[94:95]
	v_mov_b64_e32 v[24:25], v[96:97]
	v_mfma_f32_16x16x32_bf16 v[14:17], v[2:5], v[138:141], v[14:17]
	s_nop 7
	global_store_dwordx4 v[152:153], v[14:17], off offset:384
	s_nop 1
	v_pk_mul_f32 v[16:17], v[20:21], v[146:147] op_sel_hi:[1,0]
	v_pk_mul_f32 v[14:15], v[18:19], v[146:147] op_sel_hi:[1,0]
	v_mov_b64_e32 v[18:19], v[130:131]
	v_mov_b64_e32 v[20:21], v[132:133]
	v_mfma_f32_16x16x32_bf16 v[14:17], v[2:5], v[142:145], v[14:17]
	s_nop 7
	global_store_dwordx4 v[70:71], v[14:17], off offset:384
	ds_read_b128 v[14:17], v147 offset:11776
	s_waitcnt lgkmcnt(0)
	v_cndmask_b32_e64 v2, v14, 0, vcc
	v_cndmask_b32_e64 v3, v15, 0, vcc
	v_cndmask_b32_e64 v4, v16, 0, vcc
	v_cndmask_b32_e64 v14, v17, 0, vcc
	v_cvt_pk_bf16_f32 v2, v2, v3
	v_cvt_pk_bf16_f32 v3, v4, v14
	v_mov_b32_e32 v4, v5
	s_nop 1
	v_mfma_f32_16x16x32_bf16 v[6:9], v[2:5], v[138:141], v[6:9]
	v_perm_b32 v141, v211, v210, s37
	v_perm_b32 v140, v213, v212, s37
	v_perm_b32 v139, v217, v216, s37
	s_nop 4
	global_store_dwordx4 v[152:153], v[6:9], off offset:448
	s_nop 1
	v_pk_mul_f32 v[8:9], v[12:13], v[146:147] op_sel_hi:[1,0]
	v_pk_mul_f32 v[6:7], v[10:11], v[146:147] op_sel_hi:[1,0]
	s_nop 1
	v_mfma_f32_16x16x32_bf16 v[6:9], v[2:5], v[142:145], v[6:9]
	v_lshl_add_u32 v2, v190, 2, s23
	v_xor_b32_e32 v4, 1, v204
	s_nop 5
	global_store_dwordx4 v[70:71], v[6:9], off offset:448
	s_waitcnt lgkmcnt(0)
	s_barrier
	ds_read_b128 v[6:9], v2 offset:20480
	ds_read_b128 v[10:13], v188 offset:28928
	v_mov_b64_e32 v[70:71], v[74:75]
	v_mov_b64_e32 v[72:73], v[76:77]
	s_waitcnt lgkmcnt(1)
	v_pk_mul_f32 v[2:3], v[8:9], v[8:9]
	v_pk_mul_f32 v[14:15], v[6:7], v[6:7]
	s_nop 0
	v_pk_mov_b32 v[16:17], v[14:15], v[2:3] op_sel:[1,0]
	v_mov_b32_e32 v15, v3
	v_pk_add_f32 v[2:3], v[16:17], v[14:15]
	s_nop 0
	v_add_f32_e32 v2, v2, v3
	v_and_b32_e32 v3, 64, v204
	v_add_u32_e32 v3, 64, v3
	s_waitcnt lgkmcnt(0)
	s_nop 1
	v_add_f32_dpp v2, v2, v2 quad_perm:[1,0,3,2] row_mask:0xf bank_mask:0xf
	s_nop 1
	v_add_f32_dpp v2, v2, v2 quad_perm:[2,3,0,1] row_mask:0xf bank_mask:0xf
	s_nop 1
	v_add_f32_dpp v2, v2, v2 row_half_mirror row_mask:0xf bank_mask:0xf
	s_nop 1
	v_add_f32_dpp v2, v2, v2 row_mirror row_mask:0xf bank_mask:0xf
	v_xor_b32_e32 v4, 16, v204
	v_cmp_lt_i32_e32 vcc, v4, v3
	s_nop 1
	v_cndmask_b32_e32 v4, v204, v4, vcc
	v_lshlrev_b32_e32 v4, 2, v4
	ds_bpermute_b32 v4, v4, v2
	s_waitcnt lgkmcnt(0)
	v_add_f32_e32 v2, v2, v4
	v_xor_b32_e32 v4, 32, v204
	v_cmp_lt_i32_e32 vcc, v4, v3
	s_nop 1
	v_cndmask_b32_e32 v3, v204, v4, vcc
	v_lshlrev_b32_e32 v3, 2, v3
	ds_bpermute_b32 v3, v3, v2
	s_waitcnt lgkmcnt(0)
	v_add_f32_e32 v2, v2, v3
	v_fmamk_f32 v2, v2, 0x3b800000, v205
	v_mul_f32_e32 v3, 0x4f800000, v2
	v_cmp_gt_f32_e32 vcc, s36, v2
	s_nop 1
	v_cndmask_b32_e32 v2, v2, v3, vcc
	v_sqrt_f32_e32 v3, v2
	s_nop 0
	v_add_u32_e32 v4, -1, v3
	v_fma_f32 v14, -v4, v3, v2
	v_cmp_ge_f32_e64 s[0:1], 0, v14
	v_add_u32_e32 v14, 1, v3
	s_nop 0
	v_cndmask_b32_e64 v4, v3, v4, s[0:1]
	v_fma_f32 v3, -v14, v3, v2
	v_cmp_lt_f32_e64 s[0:1], 0, v3
	s_nop 1
	v_cndmask_b32_e64 v3, v4, v14, s[0:1]
	v_mul_f32_e32 v4, 0x37800000, v3
	v_cndmask_b32_e32 v3, v3, v4, vcc
	v_cmp_class_f32_e32 vcc, v2, v206
	s_nop 1
	v_cndmask_b32_e32 v2, v3, v2, vcc
	v_div_scale_f32 v3, s[0:1], v2, v2, 1.0
	v_rcp_f32_e32 v4, v3
	s_and_b32 s0, s38, -8
	s_add_i32 s0, s24, s0
	s_ashr_i32 s1, s0, 31
	v_fma_f32 v14, -v3, v4, 1.0
	v_fmac_f32_e32 v4, v14, v4
	v_div_scale_f32 v14, vcc, 1.0, v2, 1.0
	v_mul_f32_e32 v15, v14, v4
	v_fma_f32 v16, -v3, v15, v14
	v_fmac_f32_e32 v15, v16, v4
	v_fma_f32 v3, -v3, v15, v14
	s_lshl_b64 s[0:1], s[0:1], 13
	v_div_fmas_f32 v3, v3, v4, v15
	s_add_u32 s0, s80, s0
	v_div_fixup_f32 v2, v3, v2, 1.0
	s_addc_u32 s1, s81, s1
	s_lshl_b32 s4, s39, 9
	v_pk_mul_f32 v[6:7], v[6:7], v[2:3] op_sel_hi:[1,0]
	v_pk_mul_f32 v[2:3], v[8:9], v[2:3] op_sel_hi:[1,0]
	s_add_u32 s0, s0, s4
	v_pk_mul_f32 v[6:7], v[10:11], v[6:7]
	v_pk_mul_f32 v[2:3], v[12:13], v[2:3]
	s_addc_u32 s1, s1, 0
	v_cvt_pk_bf16_f32 v6, v6, v7
	v_cvt_pk_bf16_f32 v7, v2, v3
	v_lshl_add_u64 v[2:3], v[190:191], 1, s[0:1]
	v_add_co_u32_e32 v2, vcc, 0x3d201000, v2
	v_mov_b64_e32 v[14:15], v[98:99]
	s_nop 0
	v_addc_co_u32_e32 v3, vcc, 0, v3, vcc
	global_store_dwordx2 v[2:3], v[6:7], off
	s_waitcnt lgkmcnt(0)
	s_barrier
	v_mov_b64_e32 v[6:7], v[102:103]
	v_mov_b64_e32 v[10:11], v[134:135]
	v_perm_b32 v3, v215, v214, s37
	s_andn2_b64 vcc, exec, s[6:7]
	v_mov_b64_e32 v[16:17], v[100:101]
	v_mov_b64_e32 v[8:9], v[104:105]
	v_mov_b64_e32 v[12:13], v[136:137]
	s_mov_b32 s38, s12
	s_cbranch_vccz .LBB0_447
